# P3: second 16-row half of each group's sample-row pool GEMM moved from the rb==0 workgroup to the rb==1 workgroup (one pass each instead of two sequential passes on the critical workgroup)
# speedup vs baseline: 1.0151x; 1.0052x over previous
.LBB0_557:
	v_mov_b64_e32 v[34:35], s[28:29]
	v_lshl_or_b32 v104, s8, 8, v140
	v_mad_i64_i32 v[34:35], s[10:11], v32, s18, v[34:35]
	v_ashrrev_i32_e32 v105, 31, v104
	v_lshl_add_u64 v[106:107], v[34:35], 0, s[4:5]
	v_lshlrev_b64 v[34:35], 1, v[104:105]
	v_or_b32_e32 v108, 16, v104
	v_lshl_add_u64 v[36:37], v[106:107], 0, v[34:35]
	v_ashrrev_i32_e32 v109, 31, v108
	v_or_b32_e32 v110, 32, v104
	v_or_b32_e32 v112, 48, v104
	s_waitcnt lgkmcnt(0)
	s_barrier
	v_mov_b32_e32 v170, v36
	v_mov_b32_e32 v171, v37
	v_lshlrev_b64 v[132:133], 12, v[32:33]
	v_lshl_add_u64 v[130:131], v[104:105], 2, s[60:61]
	v_lshl_add_u64 v[132:133], s[30:31], 0, v[132:133]
	v_mov_b32_e32 v64, v143
	v_add_u32_e32 v103, 0x10800, v143
	v_lshl_add_u64 v[132:133], v[104:105], 1, v[132:133]
	ds_read_b128 v[174:177], v64
	ds_read_b128 v[178:181], v64 offset:64
	ds_read_b128 v[182:185], v64 offset:128
	ds_read_b128 v[186:189], v64 offset:192
	ds_read_b128 v[190:193], v64 offset:256
	ds_read_b128 v[194:197], v64 offset:320
	ds_read_b128 v[198:201], v64 offset:384
	ds_read_b128 v[202:205], v64 offset:448
	global_load_dwordx2 v[32:33], v[170:171], off
	global_load_dwordx2 v[34:35], v[170:171], off offset:32
	global_load_dwordx2 v[36:37], v[170:171], off offset:64
	global_load_dwordx2 v[38:39], v[170:171], off offset:96
	global_load_dwordx2 v[40:41], v[170:171], off offset:128
	global_load_dwordx2 v[42:43], v[170:171], off offset:160
	global_load_dwordx2 v[44:45], v[170:171], off offset:192
	global_load_dwordx2 v[46:47], v[170:171], off offset:224
	global_load_dwordx2 v[48:49], v[170:171], off offset:256
	global_load_dwordx2 v[50:51], v[170:171], off offset:288
	global_load_dwordx2 v[52:53], v[170:171], off offset:320
	global_load_dwordx2 v[54:55], v[170:171], off offset:352
	global_load_dwordx2 v[56:57], v[170:171], off offset:384
	global_load_dwordx2 v[58:59], v[170:171], off offset:416
	global_load_dwordx2 v[60:61], v[170:171], off offset:448
	global_load_dwordx2 v[62:63], v[170:171], off offset:480
	global_load_dwordx4 v[118:121], v[130:131], off
	global_load_dwordx4 v[122:125], v[130:131], off offset:64
	global_load_dwordx4 v[126:129], v[130:131], off offset:128
	s_waitcnt lgkmcnt(0)
	ds_read_b128 v[206:209], v64 offset:8448
	ds_read_b128 v[210:213], v64 offset:8512
	ds_read_b128 v[214:217], v64 offset:8576
	ds_read_b128 v[218:221], v64 offset:8640
	ds_read_b128 v[222:225], v64 offset:8704
	ds_read_b128 v[226:229], v64 offset:8768
	ds_read_b128 v[230:233], v64 offset:8832
	ds_read_b128 v[234:237], v64 offset:8896
	s_waitcnt vmcnt(26)
	v_mfma_f32_16x16x32_bf16 v[162:165], v[174:177], v[0:3], 0
	s_waitcnt vmcnt(25)
	v_mfma_f32_16x16x32_bf16 v[162:165], v[178:181], v[4:7], v[162:165]
	s_waitcnt vmcnt(24)
	v_mfma_f32_16x16x32_bf16 v[162:165], v[182:185], v[8:11], v[162:165]
	s_waitcnt vmcnt(23)
	v_mfma_f32_16x16x32_bf16 v[162:165], v[186:189], v[12:15], v[162:165]
	s_waitcnt vmcnt(22)
	v_mfma_f32_16x16x32_bf16 v[162:165], v[190:193], v[16:19], v[162:165]
	s_waitcnt vmcnt(21)
	v_mfma_f32_16x16x32_bf16 v[162:165], v[194:197], v[20:23], v[162:165]
	s_waitcnt vmcnt(20)
	v_mfma_f32_16x16x32_bf16 v[162:165], v[198:201], v[24:27], v[162:165]
	s_waitcnt vmcnt(19)
	v_mfma_f32_16x16x32_bf16 v[162:165], v[202:205], v[28:31], v[162:165]
	s_waitcnt vmcnt(18)
	v_lshlrev_b32_e32 v170, 16, v32
	v_and_b32_e32 v171, 0xffff0000, v32
	v_mul_f32_e32 v166, 0xbfb8aa3b, v170
	v_exp_f32_e32 v166, v166
	s_nop 0
	v_add_f32_e32 v166, 1.0, v166
	v_rcp_f32_e32 v172, v166
	v_mul_f32_e32 v166, 0xbfb8aa3b, v171
	v_exp_f32_e32 v166, v166
	s_nop 0
	v_add_f32_e32 v166, 1.0, v166
	v_rcp_f32_e32 v173, v166
	s_waitcnt vmcnt(2)
	v_pk_mul_f32 v[118:119], v[118:119], v[162:163]
	v_pk_mul_f32 v[120:121], v[120:121], v[164:165]
	v_pk_mul_f32 v[172:173], v[172:173], v[170:171]
	s_nop 0
	v_pk_mul_f32 v[118:119], v[172:173], v[118:119]
	s_nop 0
	v_cvt_pk_bf16_f32 v166, v118, v119
	v_lshlrev_b32_e32 v170, 16, v33
	v_and_b32_e32 v171, 0xffff0000, v33
	v_mul_f32_e32 v167, 0xbfb8aa3b, v170
	v_exp_f32_e32 v167, v167
	s_nop 0
	v_add_f32_e32 v167, 1.0, v167
	v_rcp_f32_e32 v172, v167
	v_mul_f32_e32 v167, 0xbfb8aa3b, v171
	v_exp_f32_e32 v167, v167
	s_nop 0
	v_add_f32_e32 v167, 1.0, v167
	v_rcp_f32_e32 v173, v167
	s_nop 1
	v_pk_mul_f32 v[172:173], v[172:173], v[170:171]
	s_nop 0
	v_pk_mul_f32 v[120:121], v[172:173], v[120:121]
	s_nop 0
	v_cvt_pk_bf16_f32 v167, v120, v121
	s_nop 0
	global_store_dwordx2 v[132:133], v[166:167], off offset:2048
	global_load_dwordx4 v[118:121], v[130:131], off offset:192
	s_waitcnt lgkmcnt(0)
	ds_read_b128 v[174:177], v64 offset:16896
	ds_read_b128 v[178:181], v64 offset:16960
	ds_read_b128 v[182:185], v64 offset:17024
	ds_read_b128 v[186:189], v64 offset:17088
	ds_read_b128 v[190:193], v64 offset:17152
	ds_read_b128 v[194:197], v64 offset:17216
	ds_read_b128 v[198:201], v64 offset:17280
	ds_read_b128 v[202:205], v64 offset:17344
	v_mfma_f32_16x16x32_bf16 v[162:165], v[206:209], v[0:3], 0
	v_mfma_f32_16x16x32_bf16 v[162:165], v[210:213], v[4:7], v[162:165]
	v_mfma_f32_16x16x32_bf16 v[162:165], v[214:217], v[8:11], v[162:165]
	v_mfma_f32_16x16x32_bf16 v[162:165], v[218:221], v[12:15], v[162:165]
	v_mfma_f32_16x16x32_bf16 v[162:165], v[222:225], v[16:19], v[162:165]
	v_mfma_f32_16x16x32_bf16 v[162:165], v[226:229], v[20:23], v[162:165]
	v_mfma_f32_16x16x32_bf16 v[162:165], v[230:233], v[24:27], v[162:165]
	v_mfma_f32_16x16x32_bf16 v[162:165], v[234:237], v[28:31], v[162:165]
	s_waitcnt vmcnt(19)
	v_lshlrev_b32_e32 v170, 16, v34
	v_and_b32_e32 v171, 0xffff0000, v34
	v_mul_f32_e32 v166, 0xbfb8aa3b, v170
	v_exp_f32_e32 v166, v166
	s_nop 0
	v_add_f32_e32 v166, 1.0, v166
	v_rcp_f32_e32 v172, v166
	v_mul_f32_e32 v166, 0xbfb8aa3b, v171
	v_exp_f32_e32 v166, v166
	s_nop 0
	v_add_f32_e32 v166, 1.0, v166
	v_rcp_f32_e32 v173, v166
	s_waitcnt vmcnt(3)
	v_pk_mul_f32 v[122:123], v[122:123], v[162:163]
	v_pk_mul_f32 v[124:125], v[124:125], v[164:165]
	v_pk_mul_f32 v[172:173], v[172:173], v[170:171]
	s_nop 0
	v_pk_mul_f32 v[122:123], v[172:173], v[122:123]
	s_nop 0
	v_cvt_pk_bf16_f32 v166, v122, v123
	v_lshlrev_b32_e32 v170, 16, v35
	v_and_b32_e32 v171, 0xffff0000, v35
	v_mul_f32_e32 v167, 0xbfb8aa3b, v170
	v_exp_f32_e32 v167, v167
	s_nop 0
	v_add_f32_e32 v167, 1.0, v167
	v_rcp_f32_e32 v172, v167
	v_mul_f32_e32 v167, 0xbfb8aa3b, v171
	v_exp_f32_e32 v167, v167
	s_nop 0
	v_add_f32_e32 v167, 1.0, v167
	v_rcp_f32_e32 v173, v167
	s_nop 1
	v_pk_mul_f32 v[172:173], v[172:173], v[170:171]
	s_nop 0
	v_pk_mul_f32 v[124:125], v[172:173], v[124:125]
	s_nop 0
	v_cvt_pk_bf16_f32 v167, v124, v125
	s_nop 0
	global_store_dwordx2 v[132:133], v[166:167], off offset:2080
	global_load_dwordx4 v[122:125], v[130:131], off offset:256
	s_waitcnt lgkmcnt(0)
	ds_read_b128 v[206:209], v64 offset:25344
	ds_read_b128 v[210:213], v64 offset:25408
	ds_read_b128 v[214:217], v64 offset:25472
	ds_read_b128 v[218:221], v64 offset:25536
	ds_read_b128 v[222:225], v64 offset:25600
	ds_read_b128 v[226:229], v64 offset:25664
	ds_read_b128 v[230:233], v64 offset:25728
	ds_read_b128 v[234:237], v64 offset:25792
	v_mfma_f32_16x16x32_bf16 v[162:165], v[174:177], v[0:3], 0
	v_mfma_f32_16x16x32_bf16 v[162:165], v[178:181], v[4:7], v[162:165]
	v_mfma_f32_16x16x32_bf16 v[162:165], v[182:185], v[8:11], v[162:165]
	v_mfma_f32_16x16x32_bf16 v[162:165], v[186:189], v[12:15], v[162:165]
	v_mfma_f32_16x16x32_bf16 v[162:165], v[190:193], v[16:19], v[162:165]
	v_mfma_f32_16x16x32_bf16 v[162:165], v[194:197], v[20:23], v[162:165]
	v_mfma_f32_16x16x32_bf16 v[162:165], v[198:201], v[24:27], v[162:165]
	v_mfma_f32_16x16x32_bf16 v[162:165], v[202:205], v[28:31], v[162:165]
	s_waitcnt vmcnt(20)
	v_lshlrev_b32_e32 v170, 16, v36
	v_and_b32_e32 v171, 0xffff0000, v36
	v_mul_f32_e32 v166, 0xbfb8aa3b, v170
	v_exp_f32_e32 v166, v166
	s_nop 0
	v_add_f32_e32 v166, 1.0, v166
	v_rcp_f32_e32 v172, v166
	v_mul_f32_e32 v166, 0xbfb8aa3b, v171
	v_exp_f32_e32 v166, v166
	s_nop 0
	v_add_f32_e32 v166, 1.0, v166
	v_rcp_f32_e32 v173, v166
	s_waitcnt vmcnt(4)
	v_pk_mul_f32 v[126:127], v[126:127], v[162:163]
	v_pk_mul_f32 v[128:129], v[128:129], v[164:165]
	v_pk_mul_f32 v[172:173], v[172:173], v[170:171]
	s_nop 0
	v_pk_mul_f32 v[126:127], v[172:173], v[126:127]
	s_nop 0
	v_cvt_pk_bf16_f32 v166, v126, v127
	v_lshlrev_b32_e32 v170, 16, v37
	v_and_b32_e32 v171, 0xffff0000, v37
	v_mul_f32_e32 v167, 0xbfb8aa3b, v170
	v_exp_f32_e32 v167, v167
	s_nop 0
	v_add_f32_e32 v167, 1.0, v167
	v_rcp_f32_e32 v172, v167
	v_mul_f32_e32 v167, 0xbfb8aa3b, v171
	v_exp_f32_e32 v167, v167
	s_nop 0
	v_add_f32_e32 v167, 1.0, v167
	v_rcp_f32_e32 v173, v167
	s_nop 1
	v_pk_mul_f32 v[172:173], v[172:173], v[170:171]
	s_nop 0
	v_pk_mul_f32 v[128:129], v[172:173], v[128:129]
	s_nop 0
	v_cvt_pk_bf16_f32 v167, v128, v129
	s_nop 0
	global_store_dwordx2 v[132:133], v[166:167], off offset:2112
	global_load_dwordx4 v[126:129], v[130:131], off offset:320
	s_waitcnt lgkmcnt(0)
	ds_read_b128 v[174:177], v64 offset:33792
	ds_read_b128 v[178:181], v64 offset:33856
	ds_read_b128 v[182:185], v64 offset:33920
	ds_read_b128 v[186:189], v64 offset:33984
	ds_read_b128 v[190:193], v64 offset:34048
	ds_read_b128 v[194:197], v64 offset:34112
	ds_read_b128 v[198:201], v64 offset:34176
	ds_read_b128 v[202:205], v64 offset:34240
	v_mfma_f32_16x16x32_bf16 v[162:165], v[206:209], v[0:3], 0
	v_mfma_f32_16x16x32_bf16 v[162:165], v[210:213], v[4:7], v[162:165]
	v_mfma_f32_16x16x32_bf16 v[162:165], v[214:217], v[8:11], v[162:165]
	v_mfma_f32_16x16x32_bf16 v[162:165], v[218:221], v[12:15], v[162:165]
	v_mfma_f32_16x16x32_bf16 v[162:165], v[222:225], v[16:19], v[162:165]
	v_mfma_f32_16x16x32_bf16 v[162:165], v[226:229], v[20:23], v[162:165]
	v_mfma_f32_16x16x32_bf16 v[162:165], v[230:233], v[24:27], v[162:165]
	v_mfma_f32_16x16x32_bf16 v[162:165], v[234:237], v[28:31], v[162:165]
	s_waitcnt vmcnt(21)
	v_lshlrev_b32_e32 v170, 16, v38
	v_and_b32_e32 v171, 0xffff0000, v38
	v_mul_f32_e32 v166, 0xbfb8aa3b, v170
	v_exp_f32_e32 v166, v166
	s_nop 0
	v_add_f32_e32 v166, 1.0, v166
	v_rcp_f32_e32 v172, v166
	v_mul_f32_e32 v166, 0xbfb8aa3b, v171
	v_exp_f32_e32 v166, v166
	s_nop 0
	v_add_f32_e32 v166, 1.0, v166
	v_rcp_f32_e32 v173, v166
	s_waitcnt vmcnt(4)
	v_pk_mul_f32 v[118:119], v[118:119], v[162:163]
	v_pk_mul_f32 v[120:121], v[120:121], v[164:165]
	v_pk_mul_f32 v[172:173], v[172:173], v[170:171]
	s_nop 0
	v_pk_mul_f32 v[118:119], v[172:173], v[118:119]
	s_nop 0
	v_cvt_pk_bf16_f32 v166, v118, v119
	v_lshlrev_b32_e32 v170, 16, v39
	v_and_b32_e32 v171, 0xffff0000, v39
	v_mul_f32_e32 v167, 0xbfb8aa3b, v170
	v_exp_f32_e32 v167, v167
	s_nop 0
	v_add_f32_e32 v167, 1.0, v167
	v_rcp_f32_e32 v172, v167
	v_mul_f32_e32 v167, 0xbfb8aa3b, v171
	v_exp_f32_e32 v167, v167
	s_nop 0
	v_add_f32_e32 v167, 1.0, v167
	v_rcp_f32_e32 v173, v167
	s_nop 1
	v_pk_mul_f32 v[172:173], v[172:173], v[170:171]
	s_nop 0
	v_pk_mul_f32 v[120:121], v[172:173], v[120:121]
	s_nop 0
	v_cvt_pk_bf16_f32 v167, v120, v121
	s_nop 0
	global_store_dwordx2 v[132:133], v[166:167], off offset:2144
	global_load_dwordx4 v[118:121], v[130:131], off offset:384
	s_waitcnt lgkmcnt(0)
	ds_read_b128 v[206:209], v64 offset:42240
	ds_read_b128 v[210:213], v64 offset:42304
	ds_read_b128 v[214:217], v64 offset:42368
	ds_read_b128 v[218:221], v64 offset:42432
	ds_read_b128 v[222:225], v64 offset:42496
	ds_read_b128 v[226:229], v64 offset:42560
	ds_read_b128 v[230:233], v64 offset:42624
	ds_read_b128 v[234:237], v64 offset:42688
	v_mfma_f32_16x16x32_bf16 v[162:165], v[174:177], v[0:3], 0
	v_mfma_f32_16x16x32_bf16 v[162:165], v[178:181], v[4:7], v[162:165]
	v_mfma_f32_16x16x32_bf16 v[162:165], v[182:185], v[8:11], v[162:165]
	v_mfma_f32_16x16x32_bf16 v[162:165], v[186:189], v[12:15], v[162:165]
	v_mfma_f32_16x16x32_bf16 v[162:165], v[190:193], v[16:19], v[162:165]
	v_mfma_f32_16x16x32_bf16 v[162:165], v[194:197], v[20:23], v[162:165]
	v_mfma_f32_16x16x32_bf16 v[162:165], v[198:201], v[24:27], v[162:165]
	v_mfma_f32_16x16x32_bf16 v[162:165], v[202:205], v[28:31], v[162:165]
	s_waitcnt vmcnt(22)
	v_lshlrev_b32_e32 v170, 16, v40
	v_and_b32_e32 v171, 0xffff0000, v40
	v_mul_f32_e32 v166, 0xbfb8aa3b, v170
	v_exp_f32_e32 v166, v166
	s_nop 0
	v_add_f32_e32 v166, 1.0, v166
	v_rcp_f32_e32 v172, v166
	v_mul_f32_e32 v166, 0xbfb8aa3b, v171
	v_exp_f32_e32 v166, v166
	s_nop 0
	v_add_f32_e32 v166, 1.0, v166
	v_rcp_f32_e32 v173, v166
	s_waitcnt vmcnt(4)
	v_pk_mul_f32 v[122:123], v[122:123], v[162:163]
	v_pk_mul_f32 v[124:125], v[124:125], v[164:165]
	v_pk_mul_f32 v[172:173], v[172:173], v[170:171]
	s_nop 0
	v_pk_mul_f32 v[122:123], v[172:173], v[122:123]
	s_nop 0
	v_cvt_pk_bf16_f32 v166, v122, v123
	v_lshlrev_b32_e32 v170, 16, v41
	v_and_b32_e32 v171, 0xffff0000, v41
	v_mul_f32_e32 v167, 0xbfb8aa3b, v170
	v_exp_f32_e32 v167, v167
	s_nop 0
	v_add_f32_e32 v167, 1.0, v167
	v_rcp_f32_e32 v172, v167
	v_mul_f32_e32 v167, 0xbfb8aa3b, v171
	v_exp_f32_e32 v167, v167
	s_nop 0
	v_add_f32_e32 v167, 1.0, v167
	v_rcp_f32_e32 v173, v167
	s_nop 1
	v_pk_mul_f32 v[172:173], v[172:173], v[170:171]
	s_nop 0
	v_pk_mul_f32 v[124:125], v[172:173], v[124:125]
	s_nop 0
	v_cvt_pk_bf16_f32 v167, v124, v125
	s_nop 0
	global_store_dwordx2 v[132:133], v[166:167], off offset:2176
	global_load_dwordx4 v[122:125], v[130:131], off offset:448
	s_waitcnt lgkmcnt(0)
	ds_read_b128 v[174:177], v64 offset:50688
	ds_read_b128 v[178:181], v64 offset:50752
	ds_read_b128 v[182:185], v64 offset:50816
	ds_read_b128 v[186:189], v64 offset:50880
	ds_read_b128 v[190:193], v64 offset:50944
	ds_read_b128 v[194:197], v64 offset:51008
	ds_read_b128 v[198:201], v64 offset:51072
	ds_read_b128 v[202:205], v64 offset:51136
	v_mfma_f32_16x16x32_bf16 v[162:165], v[206:209], v[0:3], 0
	v_mfma_f32_16x16x32_bf16 v[162:165], v[210:213], v[4:7], v[162:165]
	v_mfma_f32_16x16x32_bf16 v[162:165], v[214:217], v[8:11], v[162:165]
	v_mfma_f32_16x16x32_bf16 v[162:165], v[218:221], v[12:15], v[162:165]
	v_mfma_f32_16x16x32_bf16 v[162:165], v[222:225], v[16:19], v[162:165]
	v_mfma_f32_16x16x32_bf16 v[162:165], v[226:229], v[20:23], v[162:165]
	v_mfma_f32_16x16x32_bf16 v[162:165], v[230:233], v[24:27], v[162:165]
	v_mfma_f32_16x16x32_bf16 v[162:165], v[234:237], v[28:31], v[162:165]
	s_waitcnt vmcnt(23)
	v_lshlrev_b32_e32 v170, 16, v42
	v_and_b32_e32 v171, 0xffff0000, v42
	v_mul_f32_e32 v166, 0xbfb8aa3b, v170
	v_exp_f32_e32 v166, v166
	s_nop 0
	v_add_f32_e32 v166, 1.0, v166
	v_rcp_f32_e32 v172, v166
	v_mul_f32_e32 v166, 0xbfb8aa3b, v171
	v_exp_f32_e32 v166, v166
	s_nop 0
	v_add_f32_e32 v166, 1.0, v166
	v_rcp_f32_e32 v173, v166
	s_waitcnt vmcnt(4)
	v_pk_mul_f32 v[126:127], v[126:127], v[162:163]
	v_pk_mul_f32 v[128:129], v[128:129], v[164:165]
	v_pk_mul_f32 v[172:173], v[172:173], v[170:171]
	s_nop 0
	v_pk_mul_f32 v[126:127], v[172:173], v[126:127]
	s_nop 0
	v_cvt_pk_bf16_f32 v166, v126, v127
	v_lshlrev_b32_e32 v170, 16, v43
	v_and_b32_e32 v171, 0xffff0000, v43
	v_mul_f32_e32 v167, 0xbfb8aa3b, v170
	v_exp_f32_e32 v167, v167
	s_nop 0
	v_add_f32_e32 v167, 1.0, v167
	v_rcp_f32_e32 v172, v167
	v_mul_f32_e32 v167, 0xbfb8aa3b, v171
	v_exp_f32_e32 v167, v167
	s_nop 0
	v_add_f32_e32 v167, 1.0, v167
	v_rcp_f32_e32 v173, v167
	s_nop 1
	v_pk_mul_f32 v[172:173], v[172:173], v[170:171]
	s_nop 0
	v_pk_mul_f32 v[128:129], v[172:173], v[128:129]
	s_nop 0
	v_cvt_pk_bf16_f32 v167, v128, v129
	s_nop 0
	global_store_dwordx2 v[132:133], v[166:167], off offset:2208
	global_load_dwordx4 v[126:129], v[130:131], off offset:512
	s_waitcnt lgkmcnt(0)
	ds_read_b128 v[206:209], v64 offset:59136
	ds_read_b128 v[210:213], v64 offset:59200
	ds_read_b128 v[214:217], v64 offset:59264
	ds_read_b128 v[218:221], v64 offset:59328
	ds_read_b128 v[222:225], v64 offset:59392
	ds_read_b128 v[226:229], v64 offset:59456
	ds_read_b128 v[230:233], v64 offset:59520
	ds_read_b128 v[234:237], v64 offset:59584
	v_mfma_f32_16x16x32_bf16 v[162:165], v[174:177], v[0:3], 0
	v_mfma_f32_16x16x32_bf16 v[162:165], v[178:181], v[4:7], v[162:165]
	v_mfma_f32_16x16x32_bf16 v[162:165], v[182:185], v[8:11], v[162:165]
	v_mfma_f32_16x16x32_bf16 v[162:165], v[186:189], v[12:15], v[162:165]
	v_mfma_f32_16x16x32_bf16 v[162:165], v[190:193], v[16:19], v[162:165]
	v_mfma_f32_16x16x32_bf16 v[162:165], v[194:197], v[20:23], v[162:165]
	v_mfma_f32_16x16x32_bf16 v[162:165], v[198:201], v[24:27], v[162:165]
	v_mfma_f32_16x16x32_bf16 v[162:165], v[202:205], v[28:31], v[162:165]
	s_waitcnt vmcnt(24)
	v_lshlrev_b32_e32 v170, 16, v44
	v_and_b32_e32 v171, 0xffff0000, v44
	v_mul_f32_e32 v166, 0xbfb8aa3b, v170
	v_exp_f32_e32 v166, v166
	s_nop 0
	v_add_f32_e32 v166, 1.0, v166
	v_rcp_f32_e32 v172, v166
	v_mul_f32_e32 v166, 0xbfb8aa3b, v171
	v_exp_f32_e32 v166, v166
	s_nop 0
	v_add_f32_e32 v166, 1.0, v166
	v_rcp_f32_e32 v173, v166
	s_waitcnt vmcnt(4)
	v_pk_mul_f32 v[118:119], v[118:119], v[162:163]
	v_pk_mul_f32 v[120:121], v[120:121], v[164:165]
	v_pk_mul_f32 v[172:173], v[172:173], v[170:171]
	s_nop 0
	v_pk_mul_f32 v[118:119], v[172:173], v[118:119]
	s_nop 0
	v_cvt_pk_bf16_f32 v166, v118, v119
	v_lshlrev_b32_e32 v170, 16, v45
	v_and_b32_e32 v171, 0xffff0000, v45
	v_mul_f32_e32 v167, 0xbfb8aa3b, v170
	v_exp_f32_e32 v167, v167
	s_nop 0
	v_add_f32_e32 v167, 1.0, v167
	v_rcp_f32_e32 v172, v167
	v_mul_f32_e32 v167, 0xbfb8aa3b, v171
	v_exp_f32_e32 v167, v167
	s_nop 0
	v_add_f32_e32 v167, 1.0, v167
	v_rcp_f32_e32 v173, v167
	s_nop 1
	v_pk_mul_f32 v[172:173], v[172:173], v[170:171]
	s_nop 0
	v_pk_mul_f32 v[120:121], v[172:173], v[120:121]
	s_nop 0
	v_cvt_pk_bf16_f32 v167, v120, v121
	s_nop 0
	global_store_dwordx2 v[132:133], v[166:167], off offset:2240
	global_load_dwordx4 v[118:121], v[130:131], off offset:576
	s_waitcnt lgkmcnt(0)
	ds_read_b128 v[174:177], v103
	ds_read_b128 v[178:181], v103 offset:64
	ds_read_b128 v[182:185], v103 offset:128
	ds_read_b128 v[186:189], v103 offset:192
	ds_read_b128 v[190:193], v103 offset:256
	ds_read_b128 v[194:197], v103 offset:320
	ds_read_b128 v[198:201], v103 offset:384
	ds_read_b128 v[202:205], v103 offset:448
	v_mfma_f32_16x16x32_bf16 v[162:165], v[206:209], v[0:3], 0
	v_mfma_f32_16x16x32_bf16 v[162:165], v[210:213], v[4:7], v[162:165]
	v_mfma_f32_16x16x32_bf16 v[162:165], v[214:217], v[8:11], v[162:165]
	v_mfma_f32_16x16x32_bf16 v[162:165], v[218:221], v[12:15], v[162:165]
	v_mfma_f32_16x16x32_bf16 v[162:165], v[222:225], v[16:19], v[162:165]
	v_mfma_f32_16x16x32_bf16 v[162:165], v[226:229], v[20:23], v[162:165]
	v_mfma_f32_16x16x32_bf16 v[162:165], v[230:233], v[24:27], v[162:165]
	v_mfma_f32_16x16x32_bf16 v[162:165], v[234:237], v[28:31], v[162:165]
	s_waitcnt vmcnt(25)
	v_lshlrev_b32_e32 v170, 16, v46
	v_and_b32_e32 v171, 0xffff0000, v46
	v_mul_f32_e32 v166, 0xbfb8aa3b, v170
	v_exp_f32_e32 v166, v166
	s_nop 0
	v_add_f32_e32 v166, 1.0, v166
	v_rcp_f32_e32 v172, v166
	v_mul_f32_e32 v166, 0xbfb8aa3b, v171
	v_exp_f32_e32 v166, v166
	s_nop 0
	v_add_f32_e32 v166, 1.0, v166
	v_rcp_f32_e32 v173, v166
	s_waitcnt vmcnt(4)
	v_pk_mul_f32 v[122:123], v[122:123], v[162:163]
	v_pk_mul_f32 v[124:125], v[124:125], v[164:165]
	v_pk_mul_f32 v[172:173], v[172:173], v[170:171]
	s_nop 0
	v_pk_mul_f32 v[122:123], v[172:173], v[122:123]
	s_nop 0
	v_cvt_pk_bf16_f32 v166, v122, v123
	v_lshlrev_b32_e32 v170, 16, v47
	v_and_b32_e32 v171, 0xffff0000, v47
	v_mul_f32_e32 v167, 0xbfb8aa3b, v170
	v_exp_f32_e32 v167, v167
	s_nop 0
	v_add_f32_e32 v167, 1.0, v167
	v_rcp_f32_e32 v172, v167
	v_mul_f32_e32 v167, 0xbfb8aa3b, v171
	v_exp_f32_e32 v167, v167
	s_nop 0
	v_add_f32_e32 v167, 1.0, v167
	v_rcp_f32_e32 v173, v167
	s_nop 1
	v_pk_mul_f32 v[172:173], v[172:173], v[170:171]
	s_nop 0
	v_pk_mul_f32 v[124:125], v[172:173], v[124:125]
	s_nop 0
	v_cvt_pk_bf16_f32 v167, v124, v125
	s_nop 0
	global_store_dwordx2 v[132:133], v[166:167], off offset:2272
	global_load_dwordx4 v[122:125], v[130:131], off offset:640
	s_waitcnt lgkmcnt(0)
	ds_read_b128 v[206:209], v103 offset:8448
	ds_read_b128 v[210:213], v103 offset:8512
	ds_read_b128 v[214:217], v103 offset:8576
	ds_read_b128 v[218:221], v103 offset:8640
	ds_read_b128 v[222:225], v103 offset:8704
	ds_read_b128 v[226:229], v103 offset:8768
	ds_read_b128 v[230:233], v103 offset:8832
	ds_read_b128 v[234:237], v103 offset:8896
	v_mfma_f32_16x16x32_bf16 v[162:165], v[174:177], v[0:3], 0
	v_mfma_f32_16x16x32_bf16 v[162:165], v[178:181], v[4:7], v[162:165]
	v_mfma_f32_16x16x32_bf16 v[162:165], v[182:185], v[8:11], v[162:165]
	v_mfma_f32_16x16x32_bf16 v[162:165], v[186:189], v[12:15], v[162:165]
	v_mfma_f32_16x16x32_bf16 v[162:165], v[190:193], v[16:19], v[162:165]
	v_mfma_f32_16x16x32_bf16 v[162:165], v[194:197], v[20:23], v[162:165]
	v_mfma_f32_16x16x32_bf16 v[162:165], v[198:201], v[24:27], v[162:165]
	v_mfma_f32_16x16x32_bf16 v[162:165], v[202:205], v[28:31], v[162:165]
	s_waitcnt vmcnt(26)
	v_lshlrev_b32_e32 v170, 16, v48
	v_and_b32_e32 v171, 0xffff0000, v48
	v_mul_f32_e32 v166, 0xbfb8aa3b, v170
	v_exp_f32_e32 v166, v166
	s_nop 0
	v_add_f32_e32 v166, 1.0, v166
	v_rcp_f32_e32 v172, v166
	v_mul_f32_e32 v166, 0xbfb8aa3b, v171
	v_exp_f32_e32 v166, v166
	s_nop 0
	v_add_f32_e32 v166, 1.0, v166
	v_rcp_f32_e32 v173, v166
	s_waitcnt vmcnt(4)
	v_pk_mul_f32 v[126:127], v[126:127], v[162:163]
	v_pk_mul_f32 v[128:129], v[128:129], v[164:165]
	v_pk_mul_f32 v[172:173], v[172:173], v[170:171]
	s_nop 0
	v_pk_mul_f32 v[126:127], v[172:173], v[126:127]
	s_nop 0
	v_cvt_pk_bf16_f32 v166, v126, v127
	v_lshlrev_b32_e32 v170, 16, v49
	v_and_b32_e32 v171, 0xffff0000, v49
	v_mul_f32_e32 v167, 0xbfb8aa3b, v170
	v_exp_f32_e32 v167, v167
	s_nop 0
	v_add_f32_e32 v167, 1.0, v167
	v_rcp_f32_e32 v172, v167
	v_mul_f32_e32 v167, 0xbfb8aa3b, v171
	v_exp_f32_e32 v167, v167
	s_nop 0
	v_add_f32_e32 v167, 1.0, v167
	v_rcp_f32_e32 v173, v167
	s_nop 1
	v_pk_mul_f32 v[172:173], v[172:173], v[170:171]
	s_nop 0
	v_pk_mul_f32 v[128:129], v[172:173], v[128:129]
	s_nop 0
	v_cvt_pk_bf16_f32 v167, v128, v129
	s_nop 0
	global_store_dwordx2 v[132:133], v[166:167], off offset:2304
	global_load_dwordx4 v[126:129], v[130:131], off offset:704
	s_waitcnt lgkmcnt(0)
	ds_read_b128 v[174:177], v103 offset:16896
	ds_read_b128 v[178:181], v103 offset:16960
	ds_read_b128 v[182:185], v103 offset:17024
	ds_read_b128 v[186:189], v103 offset:17088
	ds_read_b128 v[190:193], v103 offset:17152
	ds_read_b128 v[194:197], v103 offset:17216
	ds_read_b128 v[198:201], v103 offset:17280
	ds_read_b128 v[202:205], v103 offset:17344
	v_mfma_f32_16x16x32_bf16 v[162:165], v[206:209], v[0:3], 0
	v_mfma_f32_16x16x32_bf16 v[162:165], v[210:213], v[4:7], v[162:165]
	v_mfma_f32_16x16x32_bf16 v[162:165], v[214:217], v[8:11], v[162:165]
	v_mfma_f32_16x16x32_bf16 v[162:165], v[218:221], v[12:15], v[162:165]
	v_mfma_f32_16x16x32_bf16 v[162:165], v[222:225], v[16:19], v[162:165]
	v_mfma_f32_16x16x32_bf16 v[162:165], v[226:229], v[20:23], v[162:165]
	v_mfma_f32_16x16x32_bf16 v[162:165], v[230:233], v[24:27], v[162:165]
	v_mfma_f32_16x16x32_bf16 v[162:165], v[234:237], v[28:31], v[162:165]
	s_waitcnt vmcnt(27)
	v_lshlrev_b32_e32 v170, 16, v50
	v_and_b32_e32 v171, 0xffff0000, v50
	v_mul_f32_e32 v166, 0xbfb8aa3b, v170
	v_exp_f32_e32 v166, v166
	s_nop 0
	v_add_f32_e32 v166, 1.0, v166
	v_rcp_f32_e32 v172, v166
	v_mul_f32_e32 v166, 0xbfb8aa3b, v171
	v_exp_f32_e32 v166, v166
	s_nop 0
	v_add_f32_e32 v166, 1.0, v166
	v_rcp_f32_e32 v173, v166
	s_waitcnt vmcnt(4)
	v_pk_mul_f32 v[118:119], v[118:119], v[162:163]
	v_pk_mul_f32 v[120:121], v[120:121], v[164:165]
	v_pk_mul_f32 v[172:173], v[172:173], v[170:171]
	s_nop 0
	v_pk_mul_f32 v[118:119], v[172:173], v[118:119]
	s_nop 0
	v_cvt_pk_bf16_f32 v166, v118, v119
	v_lshlrev_b32_e32 v170, 16, v51
	v_and_b32_e32 v171, 0xffff0000, v51
	v_mul_f32_e32 v167, 0xbfb8aa3b, v170
	v_exp_f32_e32 v167, v167
	s_nop 0
	v_add_f32_e32 v167, 1.0, v167
	v_rcp_f32_e32 v172, v167
	v_mul_f32_e32 v167, 0xbfb8aa3b, v171
	v_exp_f32_e32 v167, v167
	s_nop 0
	v_add_f32_e32 v167, 1.0, v167
	v_rcp_f32_e32 v173, v167
	s_nop 1
	v_pk_mul_f32 v[172:173], v[172:173], v[170:171]
	s_nop 0
	v_pk_mul_f32 v[120:121], v[172:173], v[120:121]
	s_nop 0
	v_cvt_pk_bf16_f32 v167, v120, v121
	s_nop 0
	global_store_dwordx2 v[132:133], v[166:167], off offset:2336
	global_load_dwordx4 v[118:121], v[130:131], off offset:768
	s_waitcnt lgkmcnt(0)
	ds_read_b128 v[206:209], v103 offset:25344
	ds_read_b128 v[210:213], v103 offset:25408
	ds_read_b128 v[214:217], v103 offset:25472
	ds_read_b128 v[218:221], v103 offset:25536
	ds_read_b128 v[222:225], v103 offset:25600
	ds_read_b128 v[226:229], v103 offset:25664
	ds_read_b128 v[230:233], v103 offset:25728
	ds_read_b128 v[234:237], v103 offset:25792
	v_mfma_f32_16x16x32_bf16 v[162:165], v[174:177], v[0:3], 0
	v_mfma_f32_16x16x32_bf16 v[162:165], v[178:181], v[4:7], v[162:165]
	v_mfma_f32_16x16x32_bf16 v[162:165], v[182:185], v[8:11], v[162:165]
	v_mfma_f32_16x16x32_bf16 v[162:165], v[186:189], v[12:15], v[162:165]
	v_mfma_f32_16x16x32_bf16 v[162:165], v[190:193], v[16:19], v[162:165]
	v_mfma_f32_16x16x32_bf16 v[162:165], v[194:197], v[20:23], v[162:165]
	v_mfma_f32_16x16x32_bf16 v[162:165], v[198:201], v[24:27], v[162:165]
	v_mfma_f32_16x16x32_bf16 v[162:165], v[202:205], v[28:31], v[162:165]
	s_waitcnt vmcnt(28)
	v_lshlrev_b32_e32 v170, 16, v52
	v_and_b32_e32 v171, 0xffff0000, v52
	v_mul_f32_e32 v166, 0xbfb8aa3b, v170
	v_exp_f32_e32 v166, v166
	s_nop 0
	v_add_f32_e32 v166, 1.0, v166
	v_rcp_f32_e32 v172, v166
	v_mul_f32_e32 v166, 0xbfb8aa3b, v171
	v_exp_f32_e32 v166, v166
	s_nop 0
	v_add_f32_e32 v166, 1.0, v166
	v_rcp_f32_e32 v173, v166
	s_waitcnt vmcnt(4)
	v_pk_mul_f32 v[122:123], v[122:123], v[162:163]
	v_pk_mul_f32 v[124:125], v[124:125], v[164:165]
	v_pk_mul_f32 v[172:173], v[172:173], v[170:171]
	s_nop 0
	v_pk_mul_f32 v[122:123], v[172:173], v[122:123]
	s_nop 0
	v_cvt_pk_bf16_f32 v166, v122, v123
	v_lshlrev_b32_e32 v170, 16, v53
	v_and_b32_e32 v171, 0xffff0000, v53
	v_mul_f32_e32 v167, 0xbfb8aa3b, v170
	v_exp_f32_e32 v167, v167
	s_nop 0
	v_add_f32_e32 v167, 1.0, v167
	v_rcp_f32_e32 v172, v167
	v_mul_f32_e32 v167, 0xbfb8aa3b, v171
	v_exp_f32_e32 v167, v167
	s_nop 0
	v_add_f32_e32 v167, 1.0, v167
	v_rcp_f32_e32 v173, v167
	s_nop 1
	v_pk_mul_f32 v[172:173], v[172:173], v[170:171]
	s_nop 0
	v_pk_mul_f32 v[124:125], v[172:173], v[124:125]
	s_nop 0
	v_cvt_pk_bf16_f32 v167, v124, v125
	s_nop 0
	global_store_dwordx2 v[132:133], v[166:167], off offset:2368
	global_load_dwordx4 v[122:125], v[130:131], off offset:832
	s_waitcnt lgkmcnt(0)
	ds_read_b128 v[174:177], v103 offset:33792
	ds_read_b128 v[178:181], v103 offset:33856
	ds_read_b128 v[182:185], v103 offset:33920
	ds_read_b128 v[186:189], v103 offset:33984
	ds_read_b128 v[190:193], v103 offset:34048
	ds_read_b128 v[194:197], v103 offset:34112
	ds_read_b128 v[198:201], v103 offset:34176
	ds_read_b128 v[202:205], v103 offset:34240
	v_mfma_f32_16x16x32_bf16 v[162:165], v[206:209], v[0:3], 0
	v_mfma_f32_16x16x32_bf16 v[162:165], v[210:213], v[4:7], v[162:165]
	v_mfma_f32_16x16x32_bf16 v[162:165], v[214:217], v[8:11], v[162:165]
	v_mfma_f32_16x16x32_bf16 v[162:165], v[218:221], v[12:15], v[162:165]
	v_mfma_f32_16x16x32_bf16 v[162:165], v[222:225], v[16:19], v[162:165]
	v_mfma_f32_16x16x32_bf16 v[162:165], v[226:229], v[20:23], v[162:165]
	v_mfma_f32_16x16x32_bf16 v[162:165], v[230:233], v[24:27], v[162:165]
	v_mfma_f32_16x16x32_bf16 v[162:165], v[234:237], v[28:31], v[162:165]
	s_waitcnt vmcnt(29)
	v_lshlrev_b32_e32 v170, 16, v54
	v_and_b32_e32 v171, 0xffff0000, v54
	v_mul_f32_e32 v166, 0xbfb8aa3b, v170
	v_exp_f32_e32 v166, v166
	s_nop 0
	v_add_f32_e32 v166, 1.0, v166
	v_rcp_f32_e32 v172, v166
	v_mul_f32_e32 v166, 0xbfb8aa3b, v171
	v_exp_f32_e32 v166, v166
	s_nop 0
	v_add_f32_e32 v166, 1.0, v166
	v_rcp_f32_e32 v173, v166
	s_waitcnt vmcnt(4)
	v_pk_mul_f32 v[126:127], v[126:127], v[162:163]
	v_pk_mul_f32 v[128:129], v[128:129], v[164:165]
	v_pk_mul_f32 v[172:173], v[172:173], v[170:171]
	s_nop 0
	v_pk_mul_f32 v[126:127], v[172:173], v[126:127]
	s_nop 0
	v_cvt_pk_bf16_f32 v166, v126, v127
	v_lshlrev_b32_e32 v170, 16, v55
	v_and_b32_e32 v171, 0xffff0000, v55
	v_mul_f32_e32 v167, 0xbfb8aa3b, v170
	v_exp_f32_e32 v167, v167
	s_nop 0
	v_add_f32_e32 v167, 1.0, v167
	v_rcp_f32_e32 v172, v167
	v_mul_f32_e32 v167, 0xbfb8aa3b, v171
	v_exp_f32_e32 v167, v167
	s_nop 0
	v_add_f32_e32 v167, 1.0, v167
	v_rcp_f32_e32 v173, v167
	s_nop 1
	v_pk_mul_f32 v[172:173], v[172:173], v[170:171]
	s_nop 0
	v_pk_mul_f32 v[128:129], v[172:173], v[128:129]
	s_nop 0
	v_cvt_pk_bf16_f32 v167, v128, v129
	s_nop 0
	global_store_dwordx2 v[132:133], v[166:167], off offset:2400
	global_load_dwordx4 v[126:129], v[130:131], off offset:896
	s_waitcnt lgkmcnt(0)
	ds_read_b128 v[206:209], v103 offset:42240
	ds_read_b128 v[210:213], v103 offset:42304
	ds_read_b128 v[214:217], v103 offset:42368
	ds_read_b128 v[218:221], v103 offset:42432
	ds_read_b128 v[222:225], v103 offset:42496
	ds_read_b128 v[226:229], v103 offset:42560
	ds_read_b128 v[230:233], v103 offset:42624
	ds_read_b128 v[234:237], v103 offset:42688
	v_mfma_f32_16x16x32_bf16 v[162:165], v[174:177], v[0:3], 0
	v_mfma_f32_16x16x32_bf16 v[162:165], v[178:181], v[4:7], v[162:165]
	v_mfma_f32_16x16x32_bf16 v[162:165], v[182:185], v[8:11], v[162:165]
	v_mfma_f32_16x16x32_bf16 v[162:165], v[186:189], v[12:15], v[162:165]
	v_mfma_f32_16x16x32_bf16 v[162:165], v[190:193], v[16:19], v[162:165]
	v_mfma_f32_16x16x32_bf16 v[162:165], v[194:197], v[20:23], v[162:165]
	v_mfma_f32_16x16x32_bf16 v[162:165], v[198:201], v[24:27], v[162:165]
	v_mfma_f32_16x16x32_bf16 v[162:165], v[202:205], v[28:31], v[162:165]
	s_waitcnt vmcnt(30)
	v_lshlrev_b32_e32 v170, 16, v56
	v_and_b32_e32 v171, 0xffff0000, v56
	v_mul_f32_e32 v166, 0xbfb8aa3b, v170
	v_exp_f32_e32 v166, v166
	s_nop 0
	v_add_f32_e32 v166, 1.0, v166
	v_rcp_f32_e32 v172, v166
	v_mul_f32_e32 v166, 0xbfb8aa3b, v171
	v_exp_f32_e32 v166, v166
	s_nop 0
	v_add_f32_e32 v166, 1.0, v166
	v_rcp_f32_e32 v173, v166
	s_waitcnt vmcnt(4)
	v_pk_mul_f32 v[118:119], v[118:119], v[162:163]
	v_pk_mul_f32 v[120:121], v[120:121], v[164:165]
	v_pk_mul_f32 v[172:173], v[172:173], v[170:171]
	s_nop 0
	v_pk_mul_f32 v[118:119], v[172:173], v[118:119]
	s_nop 0
	v_cvt_pk_bf16_f32 v166, v118, v119
	v_lshlrev_b32_e32 v170, 16, v57
	v_and_b32_e32 v171, 0xffff0000, v57
	v_mul_f32_e32 v167, 0xbfb8aa3b, v170
	v_exp_f32_e32 v167, v167
	s_nop 0
	v_add_f32_e32 v167, 1.0, v167
	v_rcp_f32_e32 v172, v167
	v_mul_f32_e32 v167, 0xbfb8aa3b, v171
	v_exp_f32_e32 v167, v167
	s_nop 0
	v_add_f32_e32 v167, 1.0, v167
	v_rcp_f32_e32 v173, v167
	s_nop 1
	v_pk_mul_f32 v[172:173], v[172:173], v[170:171]
	s_nop 0
	v_pk_mul_f32 v[120:121], v[172:173], v[120:121]
	s_nop 0
	v_cvt_pk_bf16_f32 v167, v120, v121
	s_nop 0
	global_store_dwordx2 v[132:133], v[166:167], off offset:2432
	global_load_dwordx4 v[118:121], v[130:131], off offset:960
	s_waitcnt lgkmcnt(0)
	ds_read_b128 v[174:177], v103 offset:50688
	ds_read_b128 v[178:181], v103 offset:50752
	ds_read_b128 v[182:185], v103 offset:50816
	ds_read_b128 v[186:189], v103 offset:50880
	ds_read_b128 v[190:193], v103 offset:50944
	ds_read_b128 v[194:197], v103 offset:51008
	ds_read_b128 v[198:201], v103 offset:51072
	ds_read_b128 v[202:205], v103 offset:51136
	v_mfma_f32_16x16x32_bf16 v[162:165], v[206:209], v[0:3], 0
	v_mfma_f32_16x16x32_bf16 v[162:165], v[210:213], v[4:7], v[162:165]
	v_mfma_f32_16x16x32_bf16 v[162:165], v[214:217], v[8:11], v[162:165]
	v_mfma_f32_16x16x32_bf16 v[162:165], v[218:221], v[12:15], v[162:165]
	v_mfma_f32_16x16x32_bf16 v[162:165], v[222:225], v[16:19], v[162:165]
	v_mfma_f32_16x16x32_bf16 v[162:165], v[226:229], v[20:23], v[162:165]
	v_mfma_f32_16x16x32_bf16 v[162:165], v[230:233], v[24:27], v[162:165]
	v_mfma_f32_16x16x32_bf16 v[162:165], v[234:237], v[28:31], v[162:165]
	s_waitcnt vmcnt(31)
	v_lshlrev_b32_e32 v170, 16, v58
	v_and_b32_e32 v171, 0xffff0000, v58
	v_mul_f32_e32 v166, 0xbfb8aa3b, v170
	v_exp_f32_e32 v166, v166
	s_nop 0
	v_add_f32_e32 v166, 1.0, v166
	v_rcp_f32_e32 v172, v166
	v_mul_f32_e32 v166, 0xbfb8aa3b, v171
	v_exp_f32_e32 v166, v166
	s_nop 0
	v_add_f32_e32 v166, 1.0, v166
	v_rcp_f32_e32 v173, v166
	s_waitcnt vmcnt(4)
	v_pk_mul_f32 v[122:123], v[122:123], v[162:163]
	v_pk_mul_f32 v[124:125], v[124:125], v[164:165]
	v_pk_mul_f32 v[172:173], v[172:173], v[170:171]
	s_nop 0
	v_pk_mul_f32 v[122:123], v[172:173], v[122:123]
	s_nop 0
	v_cvt_pk_bf16_f32 v166, v122, v123
	v_lshlrev_b32_e32 v170, 16, v59
	v_and_b32_e32 v171, 0xffff0000, v59
	v_mul_f32_e32 v167, 0xbfb8aa3b, v170
	v_exp_f32_e32 v167, v167
	s_nop 0
	v_add_f32_e32 v167, 1.0, v167
	v_rcp_f32_e32 v172, v167
	v_mul_f32_e32 v167, 0xbfb8aa3b, v171
	v_exp_f32_e32 v167, v167
	s_nop 0
	v_add_f32_e32 v167, 1.0, v167
	v_rcp_f32_e32 v173, v167
	s_nop 1
	v_pk_mul_f32 v[172:173], v[172:173], v[170:171]
	s_nop 0
	v_pk_mul_f32 v[124:125], v[172:173], v[124:125]
	s_nop 0
	v_cvt_pk_bf16_f32 v167, v124, v125
	s_nop 0
	global_store_dwordx2 v[132:133], v[166:167], off offset:2464
	s_waitcnt lgkmcnt(0)
	ds_read_b128 v[206:209], v103 offset:59136
	ds_read_b128 v[210:213], v103 offset:59200
	ds_read_b128 v[214:217], v103 offset:59264
	ds_read_b128 v[218:221], v103 offset:59328
	ds_read_b128 v[222:225], v103 offset:59392
	ds_read_b128 v[226:229], v103 offset:59456
	ds_read_b128 v[230:233], v103 offset:59520
	ds_read_b128 v[234:237], v103 offset:59584
	v_mfma_f32_16x16x32_bf16 v[162:165], v[174:177], v[0:3], 0
	v_mfma_f32_16x16x32_bf16 v[162:165], v[178:181], v[4:7], v[162:165]
	v_mfma_f32_16x16x32_bf16 v[162:165], v[182:185], v[8:11], v[162:165]
	v_mfma_f32_16x16x32_bf16 v[162:165], v[186:189], v[12:15], v[162:165]
	v_mfma_f32_16x16x32_bf16 v[162:165], v[190:193], v[16:19], v[162:165]
	v_mfma_f32_16x16x32_bf16 v[162:165], v[194:197], v[20:23], v[162:165]
	v_mfma_f32_16x16x32_bf16 v[162:165], v[198:201], v[24:27], v[162:165]
	v_mfma_f32_16x16x32_bf16 v[162:165], v[202:205], v[28:31], v[162:165]
	s_waitcnt vmcnt(31)
	v_lshlrev_b32_e32 v170, 16, v60
	v_and_b32_e32 v171, 0xffff0000, v60
	v_mul_f32_e32 v166, 0xbfb8aa3b, v170
	v_exp_f32_e32 v166, v166
	s_nop 0
	v_add_f32_e32 v166, 1.0, v166
	v_rcp_f32_e32 v172, v166
	v_mul_f32_e32 v166, 0xbfb8aa3b, v171
	v_exp_f32_e32 v166, v166
	s_nop 0
	v_add_f32_e32 v166, 1.0, v166
	v_rcp_f32_e32 v173, v166
	s_waitcnt vmcnt(3)
	v_pk_mul_f32 v[126:127], v[126:127], v[162:163]
	v_pk_mul_f32 v[128:129], v[128:129], v[164:165]
	v_pk_mul_f32 v[172:173], v[172:173], v[170:171]
	s_nop 0
	v_pk_mul_f32 v[126:127], v[172:173], v[126:127]
	s_nop 0
	v_cvt_pk_bf16_f32 v166, v126, v127
	v_lshlrev_b32_e32 v170, 16, v61
	v_and_b32_e32 v171, 0xffff0000, v61
	v_mul_f32_e32 v167, 0xbfb8aa3b, v170
	v_exp_f32_e32 v167, v167
	s_nop 0
	v_add_f32_e32 v167, 1.0, v167
	v_rcp_f32_e32 v172, v167
	v_mul_f32_e32 v167, 0xbfb8aa3b, v171
	v_exp_f32_e32 v167, v167
	s_nop 0
	v_add_f32_e32 v167, 1.0, v167
	v_rcp_f32_e32 v173, v167
	s_nop 1
	v_pk_mul_f32 v[172:173], v[172:173], v[170:171]
	s_nop 0
	v_pk_mul_f32 v[128:129], v[172:173], v[128:129]
	s_nop 0
	v_cvt_pk_bf16_f32 v167, v128, v129
	s_nop 0
	global_store_dwordx2 v[132:133], v[166:167], off offset:2496
	s_waitcnt lgkmcnt(0)
	v_mfma_f32_16x16x32_bf16 v[162:165], v[206:209], v[0:3], 0
	v_mfma_f32_16x16x32_bf16 v[162:165], v[210:213], v[4:7], v[162:165]
	v_mfma_f32_16x16x32_bf16 v[162:165], v[214:217], v[8:11], v[162:165]
	v_mfma_f32_16x16x32_bf16 v[162:165], v[218:221], v[12:15], v[162:165]
	v_mfma_f32_16x16x32_bf16 v[162:165], v[222:225], v[16:19], v[162:165]
	v_mfma_f32_16x16x32_bf16 v[162:165], v[226:229], v[20:23], v[162:165]
	v_mfma_f32_16x16x32_bf16 v[162:165], v[230:233], v[24:27], v[162:165]
	v_mfma_f32_16x16x32_bf16 v[162:165], v[234:237], v[28:31], v[162:165]
	s_waitcnt vmcnt(31)
	v_lshlrev_b32_e32 v170, 16, v62
	v_and_b32_e32 v171, 0xffff0000, v62
	v_mul_f32_e32 v166, 0xbfb8aa3b, v170
	v_exp_f32_e32 v166, v166
	s_nop 0
	v_add_f32_e32 v166, 1.0, v166
	v_rcp_f32_e32 v172, v166
	v_mul_f32_e32 v166, 0xbfb8aa3b, v171
	v_exp_f32_e32 v166, v166
	s_nop 0
	v_add_f32_e32 v166, 1.0, v166
	v_rcp_f32_e32 v173, v166
	s_waitcnt vmcnt(2)
	v_pk_mul_f32 v[118:119], v[118:119], v[162:163]
	v_pk_mul_f32 v[120:121], v[120:121], v[164:165]
	v_pk_mul_f32 v[172:173], v[172:173], v[170:171]
	s_nop 0
	v_pk_mul_f32 v[118:119], v[172:173], v[118:119]
	s_nop 0
	v_cvt_pk_bf16_f32 v166, v118, v119
	v_lshlrev_b32_e32 v170, 16, v63
	v_and_b32_e32 v171, 0xffff0000, v63
	v_mul_f32_e32 v167, 0xbfb8aa3b, v170
	v_exp_f32_e32 v167, v167
	s_nop 0
	v_add_f32_e32 v167, 1.0, v167
	v_rcp_f32_e32 v172, v167
	v_mul_f32_e32 v167, 0xbfb8aa3b, v171
	v_exp_f32_e32 v167, v167
	s_nop 0
	v_add_f32_e32 v167, 1.0, v167
	v_rcp_f32_e32 v173, v167
	s_nop 1
	v_pk_mul_f32 v[172:173], v[172:173], v[170:171]
	s_nop 0
	v_pk_mul_f32 v[120:121], v[172:173], v[120:121]
	s_nop 0
	v_cvt_pk_bf16_f32 v167, v120, v121
	s_nop 0
	global_store_dwordx2 v[132:133], v[166:167], off offset:2528
	s_cmp_gt_u32 s0, 1
	s_cbranch_scc1 .LBB0_554
	s_lshl_b32 s32, s0, 4
	v_mov_b32_e32 v252, 0x3000
	s_mov_b32 s13, 0

.Lp3_ready:
	buffer_inv sc1
	s_waitcnt vmcnt(0)
	ds_read_b128 v[0:3], v160
	ds_read_b128 v[4:7], v160 offset:64
	ds_read_b128 v[8:11], v160 offset:128
	ds_read_b128 v[12:15], v160 offset:192
	ds_read_b128 v[16:19], v160 offset:256
	ds_read_b128 v[20:23], v160 offset:320
	ds_read_b128 v[24:27], v160 offset:384
	ds_read_b128 v[28:31], v160 offset:448
	ds_read_b128 v[32:35], v161
	ds_read_b128 v[36:39], v161 offset:64
	ds_read_b128 v[40:43], v161 offset:128
	ds_read_b128 v[44:47], v161 offset:192
	ds_read_b128 v[48:51], v161 offset:256
	ds_read_b128 v[52:55], v161 offset:320
	ds_read_b128 v[56:59], v161 offset:384
	ds_read_b128 v[60:63], v161 offset:448
	v_add_u32_e32 v110, v104, v141
	v_add_u32_e32 v112, v104, v142
	s_lshl_b64 s[0:1], s[8:9], 14
	v_ashrrev_i32_e32 v111, 31, v110
	v_ashrrev_i32_e32 v113, 31, v112
	v_lshl_add_u64 v[106:107], v[100:101], 0, s[0:1]
	v_lshl_add_u64 v[108:109], v[110:111], 2, s[60:61]
	v_lshl_add_u64 v[104:105], v[112:113], 2, s[60:61]
	s_mov_b32 s0, s32
	s_mov_b64 s[8:9], 0
	v_lshlrev_b64 v[110:111], 1, v[110:111]
	v_lshlrev_b64 v[112:113], 1, v[112:113]
